# attention: waves 4-7 run their MFMA sections at priority 3 (waves 0-3 at 1) so the two waves of a SIMD take turns on the matrix pipe
# speedup vs baseline: 1.0126x; 1.0007x over previous
.Lskip_v2_0:
.LBB0_625:
	s_sub_i32 s73, s18, 63
	s_cmp_gt_i32 s73, s27
	s_cbranch_scc1 .LBB0_638
	s_bitcmp1_b32 s72, 0
	s_cselect_b32 s72, 0x2400, 0
	v_add_u32_e32 v32, s72, v188
	s_setprio 1
	v_readfirstlane_b32 s32, v242
	s_cmpk_gt_u32 s32, 0xff
	s_cbranch_scc0 .Lprio_14
	s_setprio 3
.Lprio_14:
	ds_read_b128 v[214:217], v32
	ds_read_b128 v[218:221], v32 offset:4608
	ds_read_b128 v[222:225], v32 offset:32
	ds_read_b128 v[226:229], v32 offset:4640
	ds_read_b128 v[230:233], v32 offset:64
	ds_read_b128 v[234:237], v32 offset:4672
	ds_read_b128 v[238:241], v32 offset:96
	ds_read_b128 v[244:247], v32 offset:4704
	s_waitcnt lgkmcnt(7)
	v_mfma_f32_32x32x16_bf16 v[114:129], v[214:217], v[146:149], v[98:113]
	s_waitcnt lgkmcnt(6)
	v_mfma_f32_32x32x16_bf16 v[130:145], v[218:221], v[146:149], v[98:113]
	s_waitcnt lgkmcnt(5)
	v_mfma_f32_32x32x16_bf16 v[114:129], v[222:225], v[150:153], v[114:129]
	s_waitcnt lgkmcnt(4)
	v_mfma_f32_32x32x16_bf16 v[130:145], v[226:229], v[150:153], v[130:145]
	s_waitcnt lgkmcnt(3)
	v_mfma_f32_32x32x16_bf16 v[114:129], v[230:233], v[154:157], v[114:129]
	s_waitcnt lgkmcnt(2)
	v_mfma_f32_32x32x16_bf16 v[130:145], v[234:237], v[154:157], v[130:145]
	s_waitcnt lgkmcnt(1)
	v_mfma_f32_32x32x16_bf16 v[114:129], v[238:241], v[158:161], v[114:129]
	s_waitcnt lgkmcnt(0)
	v_mfma_f32_32x32x16_bf16 v[130:145], v[244:247], v[158:161], v[130:145]
	s_setprio 0
	s_cmp_le_i32 s18, s76
	s_cbranch_scc1 .LBB0_628
	v_add_u32_e32 v32, s18, v190
	v_subrev_u32_e32 v200, 31, v32
	v_subrev_u32_e32 v198, 63, v32
	v_cmp_le_i32_e32 vcc, v200, v166
	s_nop 4
	v_cndmask_b32_e32 v130, v208, v130, vcc
	v_cmp_lt_i32_e32 vcc, v198, v166
	s_nop 1
	v_cndmask_b32_e32 v115, v208, v115, vcc
	v_cmp_le_i32_e32 vcc, v198, v166
	v_subrev_u32_e32 v198, 30, v32
	s_nop 0
	v_cndmask_b32_e32 v114, v208, v114, vcc
	v_cmp_le_i32_e32 vcc, v198, v166
	v_subrev_u32_e32 v198, 61, v32
	s_nop 0
	v_cndmask_b32_e32 v131, v208, v131, vcc
	v_cmp_le_i32_e32 vcc, v198, v166
	v_subrev_u32_e32 v198, 29, v32
	s_nop 0
	v_cndmask_b32_e32 v116, v208, v116, vcc
	v_cmp_le_i32_e32 vcc, v198, v166
	v_subrev_u32_e32 v198, 60, v32
	s_nop 0
	v_cndmask_b32_e32 v132, v208, v132, vcc
	v_cmp_le_i32_e32 vcc, v198, v166
	v_subrev_u32_e32 v198, 28, v32
	s_nop 0
	v_cndmask_b32_e32 v117, v208, v117, vcc
	v_cmp_le_i32_e32 vcc, v198, v166
	v_subrev_u32_e32 v198, 55, v32
	s_nop 0
	v_cndmask_b32_e32 v133, v208, v133, vcc
	v_cmp_le_i32_e32 vcc, v198, v166
	v_subrev_u32_e32 v198, 23, v32
	s_nop 0
	v_cndmask_b32_e32 v118, v208, v118, vcc
	v_cmp_le_i32_e32 vcc, v198, v166
	v_subrev_u32_e32 v198, 54, v32
	s_nop 0
	v_cndmask_b32_e32 v134, v208, v134, vcc
	v_cmp_le_i32_e32 vcc, v198, v166
	v_subrev_u32_e32 v198, 22, v32
	s_nop 0
	v_cndmask_b32_e32 v119, v208, v119, vcc
	v_cmp_le_i32_e32 vcc, v198, v166
	v_subrev_u32_e32 v198, 53, v32
	s_nop 0
	v_cndmask_b32_e32 v135, v208, v135, vcc
	v_cmp_le_i32_e32 vcc, v198, v166
	v_subrev_u32_e32 v198, 21, v32
	s_nop 0
	v_cndmask_b32_e32 v120, v208, v120, vcc
	v_cmp_le_i32_e32 vcc, v198, v166
	v_subrev_u32_e32 v198, 52, v32
	s_nop 0
	v_cndmask_b32_e32 v136, v208, v136, vcc
	v_cmp_le_i32_e32 vcc, v198, v166
	v_subrev_u32_e32 v198, 20, v32
	s_nop 0
	v_cndmask_b32_e32 v121, v208, v121, vcc
	v_cmp_le_i32_e32 vcc, v198, v166
	v_subrev_u32_e32 v198, 47, v32
	s_nop 0
	v_cndmask_b32_e32 v137, v208, v137, vcc
	v_cmp_le_i32_e32 vcc, v198, v166
	v_add_u32_e32 v198, -15, v32
	s_nop 0
	v_cndmask_b32_e32 v122, v208, v122, vcc
	v_cmp_le_i32_e32 vcc, v198, v166
	v_subrev_u32_e32 v198, 46, v32
	s_nop 0
	v_cndmask_b32_e32 v138, v208, v138, vcc
	v_cmp_le_i32_e32 vcc, v198, v166
	v_add_u32_e32 v198, -14, v32
	s_nop 0
	v_cndmask_b32_e32 v123, v208, v123, vcc
	v_cmp_le_i32_e32 vcc, v198, v166
	v_subrev_u32_e32 v198, 45, v32
	s_nop 0
	v_cndmask_b32_e32 v139, v208, v139, vcc
	v_cmp_le_i32_e32 vcc, v198, v166
	v_add_u32_e32 v198, -13, v32
	s_nop 0
	v_cndmask_b32_e32 v124, v208, v124, vcc
	v_cmp_le_i32_e32 vcc, v198, v166
	v_subrev_u32_e32 v198, 44, v32
	s_nop 0
	v_cndmask_b32_e32 v140, v208, v140, vcc
	v_cmp_le_i32_e32 vcc, v198, v166
	v_add_u32_e32 v198, -12, v32
	s_nop 0
	v_cndmask_b32_e32 v125, v208, v125, vcc
	v_cmp_le_i32_e32 vcc, v198, v166
	v_subrev_u32_e32 v198, 39, v32
	s_nop 0
	v_cndmask_b32_e32 v141, v208, v141, vcc
	v_cmp_le_i32_e32 vcc, v198, v166
	v_add_u32_e32 v198, -7, v32
	s_nop 0
	v_cndmask_b32_e32 v126, v208, v126, vcc
	v_cmp_le_i32_e32 vcc, v198, v166
	v_subrev_u32_e32 v198, 38, v32
	s_nop 0
	v_cndmask_b32_e32 v142, v208, v142, vcc
	v_cmp_le_i32_e32 vcc, v198, v166
	v_add_u32_e32 v198, -6, v32
	s_nop 0
	v_cndmask_b32_e32 v127, v208, v127, vcc
	v_cmp_le_i32_e32 vcc, v198, v166
	v_subrev_u32_e32 v198, 37, v32
	s_nop 0
	v_cndmask_b32_e32 v143, v208, v143, vcc
	v_cmp_le_i32_e32 vcc, v198, v166
	v_add_u32_e32 v198, -5, v32
	s_nop 0
	v_cndmask_b32_e32 v128, v208, v128, vcc
	v_cmp_le_i32_e32 vcc, v198, v166
	v_subrev_u32_e32 v198, 36, v32
	v_add_u32_e32 v32, -4, v32
	v_cndmask_b32_e32 v144, v208, v144, vcc
	v_cmp_le_i32_e32 vcc, v198, v166
	s_nop 1
	v_cndmask_b32_e32 v129, v208, v129, vcc
	v_cmp_le_i32_e32 vcc, v32, v166
	s_nop 1
	v_cndmask_b32_e32 v145, v208, v145, vcc

.LBB0_637:
	s_mulk_i32 s24, 0x5000
	v_add_u32_e32 v32, s24, v194
	s_setprio 1
	v_readfirstlane_b32 s32, v242
	s_cmpk_gt_u32 s32, 0xff
	s_cbranch_scc0 .Lprio_13
	s_setprio 3
.Lprio_13:
	ds_read_b64_tr_b16 v[214:215], v32 offset:18432
	ds_read_b64_tr_b16 v[216:217], v32 offset:20992
	ds_read_b64_tr_b16 v[218:219], v32 offset:18496
	ds_read_b64_tr_b16 v[220:221], v32 offset:21056
	ds_read_b64_tr_b16 v[222:223], v32 offset:18560
	ds_read_b64_tr_b16 v[224:225], v32 offset:21120
	ds_read_b64_tr_b16 v[226:227], v32 offset:18624
	ds_read_b64_tr_b16 v[228:229], v32 offset:21184
	ds_read_b64_tr_b16 v[230:231], v32 offset:23552
	ds_read_b64_tr_b16 v[232:233], v32 offset:26112
	v_exp_f32_e32 v114, v114
	v_exp_f32_e32 v115, v115
	v_exp_f32_e32 v116, v116
	v_exp_f32_e32 v117, v117
	v_exp_f32_e32 v118, v118
	v_cvt_pk_bf16_f32 v234, v114, v115
	v_exp_f32_e32 v119, v119
	v_cvt_pk_bf16_f32 v235, v116, v117
	v_exp_f32_e32 v120, v120
	v_exp_f32_e32 v121, v121
	v_cvt_pk_bf16_f32 v236, v118, v119
	s_nop 0
	v_cvt_pk_bf16_f32 v237, v120, v121
	s_nop 1
	s_waitcnt lgkmcnt(8)
	v_mfma_f32_32x32x16_bf16 v[82:97], v[234:237], v[214:217], v[82:97]
	ds_read_b64_tr_b16 v[214:215], v32 offset:23616
	ds_read_b64_tr_b16 v[216:217], v32 offset:26176
	v_exp_f32_e32 v122, v122
	v_exp_f32_e32 v123, v123
	v_exp_f32_e32 v124, v124
	s_waitcnt lgkmcnt(8)
	v_mfma_f32_32x32x16_bf16 v[66:81], v[234:237], v[218:221], v[66:81]
	ds_read_b64_tr_b16 v[218:219], v32 offset:23680
	ds_read_b64_tr_b16 v[220:221], v32 offset:26240
	v_exp_f32_e32 v125, v125
	v_exp_f32_e32 v126, v126
	v_exp_f32_e32 v127, v127
	v_cvt_pk_bf16_f32 v238, v122, v123
	v_add_f32_e32 v252, v114, v115
	s_waitcnt lgkmcnt(8)
	v_mfma_f32_32x32x16_bf16 v[50:65], v[234:237], v[222:225], v[50:65]
	ds_read_b64_tr_b16 v[222:223], v32 offset:23744
	ds_read_b64_tr_b16 v[224:225], v32 offset:26304
	v_exp_f32_e32 v128, v128
	v_exp_f32_e32 v129, v129
	v_cvt_pk_bf16_f32 v239, v124, v125
	v_add_f32_e32 v253, v116, v117
	s_waitcnt lgkmcnt(8)
	v_mfma_f32_32x32x16_bf16 v[34:49], v[234:237], v[226:229], v[34:49]
	ds_read_b64_tr_b16 v[226:227], v32 offset:28672
	ds_read_b64_tr_b16 v[228:229], v32 offset:31232
	v_cvt_pk_bf16_f32 v240, v126, v127
	v_cvt_pk_bf16_f32 v241, v128, v129
	v_add_f32_e32 v254, v118, v119
	v_add_f32_e32 v213, v120, v121
	s_waitcnt lgkmcnt(8)
	v_mfma_f32_32x32x16_bf16 v[82:97], v[238:241], v[230:233], v[82:97]
	ds_read_b64_tr_b16 v[230:231], v32 offset:28736
	ds_read_b64_tr_b16 v[232:233], v32 offset:31296
	v_exp_f32_e32 v130, v130
	v_exp_f32_e32 v131, v131
	v_exp_f32_e32 v132, v132
	v_add_f32_e32 v252, v252, v122
	s_waitcnt lgkmcnt(8)
	v_mfma_f32_32x32x16_bf16 v[66:81], v[238:241], v[214:217], v[66:81]
	ds_read_b64_tr_b16 v[214:215], v32 offset:28800
	ds_read_b64_tr_b16 v[216:217], v32 offset:31360
	v_exp_f32_e32 v133, v133
	v_exp_f32_e32 v134, v134
	v_exp_f32_e32 v135, v135
	v_cvt_pk_bf16_f32 v244, v130, v131
	v_add_f32_e32 v253, v253, v123
	s_waitcnt lgkmcnt(8)
	v_mfma_f32_32x32x16_bf16 v[50:65], v[238:241], v[218:221], v[50:65]
	ds_read_b64_tr_b16 v[218:219], v32 offset:28864
	ds_read_b64_tr_b16 v[220:221], v32 offset:31424
	v_exp_f32_e32 v136, v136
	v_exp_f32_e32 v137, v137
	v_cvt_pk_bf16_f32 v245, v132, v133
	v_add_f32_e32 v254, v254, v124
	v_add_f32_e32 v213, v213, v125
	s_waitcnt lgkmcnt(8)
	v_mfma_f32_32x32x16_bf16 v[34:49], v[238:241], v[222:225], v[34:49]
	ds_read_b64_tr_b16 v[222:223], v32 offset:33792
	ds_read_b64_tr_b16 v[224:225], v32 offset:36352
	v_cvt_pk_bf16_f32 v246, v134, v135
	v_add_f32_e32 v252, v252, v126
	v_cvt_pk_bf16_f32 v247, v136, v137
	v_add_f32_e32 v253, v253, v127
	v_add_f32_e32 v254, v254, v128
	v_add_f32_e32 v213, v213, v129
	s_waitcnt lgkmcnt(8)
	v_mfma_f32_32x32x16_bf16 v[82:97], v[244:247], v[226:229], v[82:97]
	ds_read_b64_tr_b16 v[226:227], v32 offset:33856
	ds_read_b64_tr_b16 v[228:229], v32 offset:36416
	v_exp_f32_e32 v138, v138
	v_exp_f32_e32 v139, v139
	v_exp_f32_e32 v140, v140
	v_add_f32_e32 v252, v252, v130
	s_waitcnt lgkmcnt(8)
	v_mfma_f32_32x32x16_bf16 v[66:81], v[244:247], v[230:233], v[66:81]
	ds_read_b64_tr_b16 v[230:231], v32 offset:33920
	ds_read_b64_tr_b16 v[232:233], v32 offset:36480
	v_exp_f32_e32 v141, v141
	v_exp_f32_e32 v142, v142
	v_exp_f32_e32 v143, v143
	v_cvt_pk_bf16_f32 v248, v138, v139
	v_add_f32_e32 v253, v253, v131
	s_waitcnt lgkmcnt(8)
	v_mfma_f32_32x32x16_bf16 v[50:65], v[244:247], v[214:217], v[50:65]
	ds_read_b64_tr_b16 v[214:215], v32 offset:33984
	ds_read_b64_tr_b16 v[216:217], v32 offset:36544
	v_exp_f32_e32 v144, v144
	v_exp_f32_e32 v145, v145
	v_cvt_pk_bf16_f32 v249, v140, v141
	v_add_f32_e32 v254, v254, v132
	v_add_f32_e32 v213, v213, v133
	s_waitcnt lgkmcnt(8)
	v_mfma_f32_32x32x16_bf16 v[34:49], v[244:247], v[218:221], v[34:49]
	v_cvt_pk_bf16_f32 v250, v142, v143
	v_add_f32_e32 v252, v252, v134
	v_cvt_pk_bf16_f32 v251, v144, v145
	v_add_f32_e32 v253, v253, v135
	v_add_f32_e32 v254, v254, v136
	v_add_f32_e32 v213, v213, v137
	s_waitcnt lgkmcnt(6)
	v_mfma_f32_32x32x16_bf16 v[82:97], v[248:251], v[222:225], v[82:97]
	v_add_f32_e32 v252, v252, v138
	v_add_f32_e32 v253, v253, v139
	v_add_f32_e32 v254, v254, v140
	s_waitcnt lgkmcnt(4)
	v_mfma_f32_32x32x16_bf16 v[66:81], v[248:251], v[226:229], v[66:81]
	v_add_f32_e32 v213, v213, v141
	v_add_f32_e32 v252, v252, v142
	v_add_f32_e32 v253, v253, v143
	s_waitcnt lgkmcnt(2)
	v_mfma_f32_32x32x16_bf16 v[50:65], v[248:251], v[230:233], v[50:65]
	v_add_f32_e32 v254, v254, v144
	v_add_f32_e32 v213, v213, v145
	v_add_f32_e32 v252, v252, v253
	v_add_f32_e32 v254, v254, v213
	s_waitcnt lgkmcnt(0)
	v_mfma_f32_32x32x16_bf16 v[34:49], v[248:251], v[214:217], v[34:49]
	v_add_f32_e32 v252, v252, v254
	v_add_f32_e32 v182, v182, v252
	s_setprio 0

.Lskip_v2_1:
.LBB0_825:
	s_sub_i32 s73, s18, 63
	s_cmp_gt_i32 s73, s26
	s_cbranch_scc1 .LBB0_838
	s_bitcmp1_b32 s72, 0
	s_cselect_b32 s72, 0x2400, 0
	v_add_u32_e32 v32, s72, v188
	s_setprio 1
	v_readfirstlane_b32 s32, v242
	s_cmpk_gt_u32 s32, 0xff
	s_cbranch_scc0 .Lprio_12
	s_setprio 3

.LBB0_837:
	s_mulk_i32 s35, 0x5000
	v_add_u32_e32 v32, s35, v194
	s_setprio 1
	v_readfirstlane_b32 s32, v242
	s_cmpk_gt_u32 s32, 0xff
	s_cbranch_scc0 .Lprio_11
	s_setprio 3

.Lskip_v2_2_p0:
.LBB0_2155_p0:
	s_sub_i32 s61, s75, 63
	s_cmp_gt_i32 s61, s25
	s_cbranch_scc1 .Lnovis_p0
	s_bitcmp1_b32 s60, 0
	s_cselect_b32 s60, 0x6400, 0
	v_add_u32_e32 v0, s60, v200
	s_setprio 1
	v_readfirstlane_b32 s32, v242
	s_cmpk_gt_u32 s32, 0xff
	s_cbranch_scc0 .Lprio_10
	s_setprio 3
.Lprio_10:
	ds_read_b128 v[238:241], v0
	ds_read_b128 v[244:247], v0 offset:32
	ds_read_b128 v[248:251], v0 offset:12800
	ds_read_b128 v[8:11], v0 offset:12832
	ds_read_b128 v[12:15], v0 offset:64
	s_waitcnt lgkmcnt(4)
	v_mfma_f32_32x32x16_bf16 v[96:111], v[238:241], v[128:131], v[80:95]
	ds_read_b128 v[238:241], v0 offset:12864
	s_waitcnt lgkmcnt(4)
	v_mfma_f32_32x32x16_bf16 v[96:111], v[244:247], v[132:135], v[96:111]
	ds_read_b128 v[244:247], v0 offset:96
	s_waitcnt lgkmcnt(4)
	v_mfma_f32_32x32x16_bf16 v[112:127], v[248:251], v[128:131], v[80:95]
	ds_read_b128 v[248:251], v0 offset:12896
	s_waitcnt lgkmcnt(4)
	v_mfma_f32_32x32x16_bf16 v[112:127], v[8:11], v[132:135], v[112:127]
	ds_read_b128 v[8:11], v0 offset:128
	s_waitcnt lgkmcnt(4)
	v_mfma_f32_32x32x16_bf16 v[96:111], v[12:15], v[136:139], v[96:111]
	ds_read_b128 v[12:15], v0 offset:12928
	s_waitcnt lgkmcnt(4)
	v_mfma_f32_32x32x16_bf16 v[112:127], v[238:241], v[136:139], v[112:127]
	ds_read_b128 v[238:241], v0 offset:160
	s_waitcnt lgkmcnt(4)
	v_mfma_f32_32x32x16_bf16 v[96:111], v[244:247], v[140:143], v[96:111]
	ds_read_b128 v[244:247], v0 offset:12960
	s_waitcnt lgkmcnt(4)
	v_mfma_f32_32x32x16_bf16 v[112:127], v[248:251], v[140:143], v[112:127]
	ds_read_b128 v[248:251], v0 offset:192
	s_waitcnt lgkmcnt(4)
	v_mfma_f32_32x32x16_bf16 v[96:111], v[8:11], v[144:147], v[96:111]
	ds_read_b128 v[8:11], v0 offset:12992
	s_waitcnt lgkmcnt(4)
	v_mfma_f32_32x32x16_bf16 v[112:127], v[12:15], v[144:147], v[112:127]
	ds_read_b128 v[12:15], v0 offset:224
	s_waitcnt lgkmcnt(4)
	v_mfma_f32_32x32x16_bf16 v[96:111], v[238:241], v[148:151], v[96:111]
	ds_read_b128 v[238:241], v0 offset:13024
	s_waitcnt lgkmcnt(4)
	v_mfma_f32_32x32x16_bf16 v[112:127], v[244:247], v[148:151], v[112:127]
	ds_read_b128 v[244:247], v0 offset:256
	s_waitcnt lgkmcnt(4)
	v_mfma_f32_32x32x16_bf16 v[96:111], v[248:251], v[152:155], v[96:111]
	ds_read_b128 v[248:251], v0 offset:13056
	s_waitcnt lgkmcnt(4)
	v_mfma_f32_32x32x16_bf16 v[112:127], v[8:11], v[152:155], v[112:127]
	ds_read_b128 v[8:11], v0 offset:288
	s_waitcnt lgkmcnt(4)
	v_mfma_f32_32x32x16_bf16 v[96:111], v[12:15], v[156:159], v[96:111]
	ds_read_b128 v[12:15], v0 offset:13088
	s_waitcnt lgkmcnt(4)
	v_mfma_f32_32x32x16_bf16 v[112:127], v[238:241], v[156:159], v[112:127]
	ds_read_b128 v[238:241], v0 offset:320
	s_waitcnt lgkmcnt(4)
	v_mfma_f32_32x32x16_bf16 v[96:111], v[244:247], v[160:163], v[96:111]
	ds_read_b128 v[244:247], v0 offset:13120
	s_waitcnt lgkmcnt(4)
	v_mfma_f32_32x32x16_bf16 v[112:127], v[248:251], v[160:163], v[112:127]
	ds_read_b128 v[248:251], v0 offset:352
	s_waitcnt lgkmcnt(4)
	v_mfma_f32_32x32x16_bf16 v[96:111], v[8:11], v[164:167], v[96:111]
	ds_read_b128 v[8:11], v0 offset:13152
	s_waitcnt lgkmcnt(4)
	v_mfma_f32_32x32x16_bf16 v[112:127], v[12:15], v[164:167], v[112:127]
	s_waitcnt lgkmcnt(3)
	v_mfma_f32_32x32x16_bf16 v[96:111], v[238:241], v[168:171], v[96:111]
	s_waitcnt lgkmcnt(2)
	v_mfma_f32_32x32x16_bf16 v[112:127], v[244:247], v[168:171], v[112:127]
	s_waitcnt lgkmcnt(1)
	v_mfma_f32_32x32x16_bf16 v[96:111], v[248:251], v[172:175], v[96:111]
	s_waitcnt lgkmcnt(0)
	v_mfma_f32_32x32x16_bf16 v[112:127], v[8:11], v[172:175], v[112:127]
	s_setprio 0
	s_cmp_le_i32 s75, s68
	s_cbranch_scc1 .Lmaskdone_p0
	v_add_u32_e32 v0, s75, v201
	v_subrev_u32_e32 v4, 31, v0
	v_subrev_u32_e32 v3, 63, v0
	v_cmp_le_i32_e32 vcc, v4, v197
	s_nop 4
	v_cndmask_b32_e32 v112, v194, v112, vcc
	v_cmp_lt_i32_e32 vcc, v3, v197
	s_nop 1
	v_cndmask_b32_e32 v97, v194, v97, vcc
	v_cmp_le_i32_e32 vcc, v3, v197
	v_subrev_u32_e32 v3, 30, v0
	s_nop 0
	v_cndmask_b32_e32 v96, v194, v96, vcc
	v_cmp_le_i32_e32 vcc, v3, v197
	v_subrev_u32_e32 v3, 61, v0
	s_nop 0
	v_cndmask_b32_e32 v113, v194, v113, vcc
	v_cmp_le_i32_e32 vcc, v3, v197
	v_subrev_u32_e32 v3, 29, v0
	s_nop 0
	v_cndmask_b32_e32 v98, v194, v98, vcc
	v_cmp_le_i32_e32 vcc, v3, v197
	v_subrev_u32_e32 v3, 60, v0
	s_nop 0
	v_cndmask_b32_e32 v114, v194, v114, vcc
	v_cmp_le_i32_e32 vcc, v3, v197
	v_subrev_u32_e32 v3, 28, v0
	s_nop 0
	v_cndmask_b32_e32 v99, v194, v99, vcc
	v_cmp_le_i32_e32 vcc, v3, v197
	v_subrev_u32_e32 v3, 55, v0
	s_nop 0
	v_cndmask_b32_e32 v115, v194, v115, vcc
	v_cmp_le_i32_e32 vcc, v3, v197
	v_subrev_u32_e32 v3, 23, v0
	s_nop 0
	v_cndmask_b32_e32 v100, v194, v100, vcc
	v_cmp_le_i32_e32 vcc, v3, v197
	v_subrev_u32_e32 v3, 54, v0
	s_nop 0
	v_cndmask_b32_e32 v116, v194, v116, vcc
	v_cmp_le_i32_e32 vcc, v3, v197
	v_subrev_u32_e32 v3, 22, v0
	s_nop 0
	v_cndmask_b32_e32 v101, v194, v101, vcc
	v_cmp_le_i32_e32 vcc, v3, v197
	v_subrev_u32_e32 v3, 53, v0
	s_nop 0
	v_cndmask_b32_e32 v117, v194, v117, vcc
	v_cmp_le_i32_e32 vcc, v3, v197
	v_subrev_u32_e32 v3, 21, v0
	s_nop 0
	v_cndmask_b32_e32 v102, v194, v102, vcc
	v_cmp_le_i32_e32 vcc, v3, v197
	v_subrev_u32_e32 v3, 52, v0
	s_nop 0
	v_cndmask_b32_e32 v118, v194, v118, vcc
	v_cmp_le_i32_e32 vcc, v3, v197
	v_subrev_u32_e32 v3, 20, v0
	s_nop 0
	v_cndmask_b32_e32 v103, v194, v103, vcc
	v_cmp_le_i32_e32 vcc, v3, v197
	v_subrev_u32_e32 v3, 47, v0
	s_nop 0
	v_cndmask_b32_e32 v119, v194, v119, vcc
	v_cmp_le_i32_e32 vcc, v3, v197
	v_add_u32_e32 v3, -15, v0
	s_nop 0
	v_cndmask_b32_e32 v104, v194, v104, vcc
	v_cmp_le_i32_e32 vcc, v3, v197
	v_subrev_u32_e32 v3, 46, v0
	s_nop 0
	v_cndmask_b32_e32 v120, v194, v120, vcc
	v_cmp_le_i32_e32 vcc, v3, v197
	v_add_u32_e32 v3, -14, v0
	s_nop 0
	v_cndmask_b32_e32 v105, v194, v105, vcc
	v_cmp_le_i32_e32 vcc, v3, v197
	v_subrev_u32_e32 v3, 45, v0
	s_nop 0
	v_cndmask_b32_e32 v121, v194, v121, vcc
	v_cmp_le_i32_e32 vcc, v3, v197
	v_add_u32_e32 v3, -13, v0
	s_nop 0
	v_cndmask_b32_e32 v106, v194, v106, vcc
	v_cmp_le_i32_e32 vcc, v3, v197
	v_subrev_u32_e32 v3, 44, v0
	s_nop 0
	v_cndmask_b32_e32 v122, v194, v122, vcc
	v_cmp_le_i32_e32 vcc, v3, v197
	v_add_u32_e32 v3, -12, v0
	s_nop 0
	v_cndmask_b32_e32 v107, v194, v107, vcc
	v_cmp_le_i32_e32 vcc, v3, v197
	v_subrev_u32_e32 v3, 39, v0
	s_nop 0
	v_cndmask_b32_e32 v123, v194, v123, vcc
	v_cmp_le_i32_e32 vcc, v3, v197
	v_add_u32_e32 v3, -7, v0
	s_nop 0
	v_cndmask_b32_e32 v108, v194, v108, vcc
	v_cmp_le_i32_e32 vcc, v3, v197
	v_subrev_u32_e32 v3, 38, v0
	s_nop 0
	v_cndmask_b32_e32 v124, v194, v124, vcc
	v_cmp_le_i32_e32 vcc, v3, v197
	v_add_u32_e32 v3, -6, v0
	s_nop 0
	v_cndmask_b32_e32 v109, v194, v109, vcc
	v_cmp_le_i32_e32 vcc, v3, v197
	v_subrev_u32_e32 v3, 37, v0
	s_nop 0
	v_cndmask_b32_e32 v125, v194, v125, vcc
	v_cmp_le_i32_e32 vcc, v3, v197
	v_add_u32_e32 v3, -5, v0
	s_nop 0
	v_cndmask_b32_e32 v110, v194, v110, vcc
	v_cmp_le_i32_e32 vcc, v3, v197
	v_subrev_u32_e32 v3, 36, v0
	v_add_u32_e32 v0, -4, v0
	v_cndmask_b32_e32 v126, v194, v126, vcc
	v_cmp_le_i32_e32 vcc, v3, v197
	s_nop 1
	v_cndmask_b32_e32 v111, v194, v111, vcc
	v_cmp_le_i32_e32 vcc, v0, v197
	s_nop 1
	v_cndmask_b32_e32 v127, v194, v127, vcc

.Lprio_9:
	ds_read_b128 v[238:241], v0
	ds_read_b128 v[244:247], v0 offset:32
	ds_read_b128 v[248:251], v0 offset:12800
	ds_read_b128 v[8:11], v0 offset:12832
	ds_read_b128 v[12:15], v0 offset:64
	s_waitcnt lgkmcnt(4)
	v_mfma_f32_32x32x16_bf16 v[206:221], v[238:241], v[128:131], v[80:95]
	ds_read_b128 v[238:241], v0 offset:12864
	v_exp_f32_e32 v96, v96
	v_exp_f32_e32 v97, v97
	v_exp_f32_e32 v98, v98
	v_exp_f32_e32 v99, v99
	s_waitcnt lgkmcnt(4)
	v_mfma_f32_32x32x16_bf16 v[206:221], v[244:247], v[132:135], v[206:221]
	ds_read_b128 v[244:247], v0 offset:96
	v_exp_f32_e32 v100, v100
	v_exp_f32_e32 v101, v101
	v_exp_f32_e32 v102, v102
	s_waitcnt lgkmcnt(4)
	v_mfma_f32_32x32x16_bf16 v[222:237], v[248:251], v[128:131], v[80:95]
	ds_read_b128 v[248:251], v0 offset:12896
	v_exp_f32_e32 v103, v103
	v_exp_f32_e32 v104, v104
	v_exp_f32_e32 v105, v105
	s_waitcnt lgkmcnt(4)
	v_mfma_f32_32x32x16_bf16 v[222:237], v[8:11], v[132:135], v[222:237]
	ds_read_b128 v[8:11], v0 offset:128
	v_exp_f32_e32 v106, v106
	v_exp_f32_e32 v107, v107
	v_exp_f32_e32 v108, v108
	v_exp_f32_e32 v109, v109
	s_waitcnt lgkmcnt(4)
	v_mfma_f32_32x32x16_bf16 v[206:221], v[12:15], v[136:139], v[206:221]
	ds_read_b128 v[12:15], v0 offset:12928
	v_exp_f32_e32 v110, v110
	v_exp_f32_e32 v111, v111
	v_add_f32_e32 v252, v96, v97
	s_waitcnt lgkmcnt(4)
	v_mfma_f32_32x32x16_bf16 v[222:237], v[238:241], v[136:139], v[222:237]
	ds_read_b128 v[238:241], v0 offset:160
	v_add_f32_e32 v253, v98, v99
	v_add_f32_e32 v254, v100, v101
	v_add_f32_e32 v205, v102, v103
	s_waitcnt lgkmcnt(4)
	v_mfma_f32_32x32x16_bf16 v[206:221], v[244:247], v[140:143], v[206:221]
	ds_read_b128 v[244:247], v0 offset:12960
	v_cvt_pk_bf16_f32 v96, v96, v97
	v_cvt_pk_bf16_f32 v97, v98, v99
	v_cvt_pk_bf16_f32 v98, v100, v101
	v_cvt_pk_bf16_f32 v99, v102, v103
	s_waitcnt lgkmcnt(4)
	v_mfma_f32_32x32x16_bf16 v[222:237], v[248:251], v[140:143], v[222:237]
	ds_read_b128 v[248:251], v0 offset:192
	v_exp_f32_e32 v112, v112
	v_exp_f32_e32 v113, v113
	v_exp_f32_e32 v114, v114
	s_waitcnt lgkmcnt(4)
	v_mfma_f32_32x32x16_bf16 v[206:221], v[8:11], v[144:147], v[206:221]
	ds_read_b128 v[8:11], v0 offset:12992
	v_exp_f32_e32 v115, v115
	v_exp_f32_e32 v116, v116
	v_exp_f32_e32 v117, v117
	s_waitcnt lgkmcnt(4)
	v_mfma_f32_32x32x16_bf16 v[222:237], v[12:15], v[144:147], v[222:237]
	ds_read_b128 v[12:15], v0 offset:224
	v_exp_f32_e32 v118, v118
	v_exp_f32_e32 v119, v119
	v_add_f32_e32 v252, v252, v104
	v_add_f32_e32 v253, v253, v105
	s_waitcnt lgkmcnt(4)
	v_mfma_f32_32x32x16_bf16 v[206:221], v[238:241], v[148:151], v[206:221]
	ds_read_b128 v[238:241], v0 offset:13024
	v_add_f32_e32 v254, v254, v106
	v_add_f32_e32 v205, v205, v107
	v_add_f32_e32 v252, v252, v108
	s_waitcnt lgkmcnt(4)
	v_mfma_f32_32x32x16_bf16 v[222:237], v[244:247], v[148:151], v[222:237]
	ds_read_b128 v[244:247], v0 offset:256
	v_add_f32_e32 v253, v253, v109
	v_add_f32_e32 v254, v254, v110
	v_add_f32_e32 v205, v205, v111
	s_waitcnt lgkmcnt(4)
	v_mfma_f32_32x32x16_bf16 v[206:221], v[248:251], v[152:155], v[206:221]
	ds_read_b128 v[248:251], v0 offset:13056
	v_cvt_pk_bf16_f32 v104, v104, v105
	v_cvt_pk_bf16_f32 v105, v106, v107
	v_cvt_pk_bf16_f32 v106, v108, v109
	v_cvt_pk_bf16_f32 v107, v110, v111
	s_waitcnt lgkmcnt(4)
	v_mfma_f32_32x32x16_bf16 v[222:237], v[8:11], v[152:155], v[222:237]
	ds_read_b128 v[8:11], v0 offset:288
	v_exp_f32_e32 v120, v120
	v_exp_f32_e32 v121, v121
	v_exp_f32_e32 v122, v122
	s_waitcnt lgkmcnt(4)
	v_mfma_f32_32x32x16_bf16 v[206:221], v[12:15], v[156:159], v[206:221]
	ds_read_b128 v[12:15], v0 offset:13088
	v_exp_f32_e32 v123, v123
	v_exp_f32_e32 v124, v124
	v_exp_f32_e32 v125, v125
	s_waitcnt lgkmcnt(4)
	v_mfma_f32_32x32x16_bf16 v[222:237], v[238:241], v[156:159], v[222:237]
	ds_read_b128 v[238:241], v0 offset:320
	v_exp_f32_e32 v126, v126
	v_exp_f32_e32 v127, v127
	v_add_f32_e32 v252, v252, v112
	v_add_f32_e32 v253, v253, v113
	s_waitcnt lgkmcnt(4)
	v_mfma_f32_32x32x16_bf16 v[206:221], v[244:247], v[160:163], v[206:221]
	ds_read_b128 v[244:247], v0 offset:13120
	v_add_f32_e32 v254, v254, v114
	v_add_f32_e32 v205, v205, v115
	v_add_f32_e32 v252, v252, v116
	s_waitcnt lgkmcnt(4)
	v_mfma_f32_32x32x16_bf16 v[222:237], v[248:251], v[160:163], v[222:237]
	ds_read_b128 v[248:251], v0 offset:352
	v_add_f32_e32 v253, v253, v117
	v_add_f32_e32 v254, v254, v118
	v_add_f32_e32 v205, v205, v119
	s_waitcnt lgkmcnt(4)
	v_mfma_f32_32x32x16_bf16 v[206:221], v[8:11], v[164:167], v[206:221]
	ds_read_b128 v[8:11], v0 offset:13152
	v_cvt_pk_bf16_f32 v112, v112, v113
	v_cvt_pk_bf16_f32 v113, v114, v115
	v_cvt_pk_bf16_f32 v114, v116, v117
	v_cvt_pk_bf16_f32 v115, v118, v119
	s_waitcnt lgkmcnt(4)
	v_mfma_f32_32x32x16_bf16 v[222:237], v[12:15], v[164:167], v[222:237]
	v_add_f32_e32 v252, v252, v120
	v_add_f32_e32 v253, v253, v121
	v_add_f32_e32 v254, v254, v122
	s_waitcnt lgkmcnt(3)
	v_mfma_f32_32x32x16_bf16 v[206:221], v[238:241], v[168:171], v[206:221]
	v_add_f32_e32 v205, v205, v123
	v_add_f32_e32 v252, v252, v124
	v_add_f32_e32 v253, v253, v125
	s_waitcnt lgkmcnt(2)
	v_mfma_f32_32x32x16_bf16 v[222:237], v[244:247], v[168:171], v[222:237]
	v_add_f32_e32 v254, v254, v126
	v_add_f32_e32 v205, v205, v127
	v_cvt_pk_bf16_f32 v120, v120, v121
	v_cvt_pk_bf16_f32 v121, v122, v123
	s_waitcnt lgkmcnt(1)
	v_mfma_f32_32x32x16_bf16 v[206:221], v[248:251], v[172:175], v[206:221]
	v_cvt_pk_bf16_f32 v122, v124, v125
	v_cvt_pk_bf16_f32 v123, v126, v127
	v_add_f32_e32 v252, v252, v253
	s_waitcnt lgkmcnt(0)
	v_mfma_f32_32x32x16_bf16 v[222:237], v[8:11], v[172:175], v[222:237]
	v_add_f32_e32 v254, v254, v205
	v_add_f32_e32 v252, v252, v254
	v_add_f32_e32 v2, v2, v252
	s_setprio 0
	s_cmp_le_i32 s75, s68
	s_cbranch_scc1 .Lmaskdone_ba
	v_add_u32_e32 v0, s75, v201
	v_subrev_u32_e32 v4, 31, v0
	v_subrev_u32_e32 v3, 63, v0
	v_cmp_le_i32_e32 vcc, v4, v197
	s_nop 4
	v_cndmask_b32_e32 v222, v194, v222, vcc
	v_cmp_lt_i32_e32 vcc, v3, v197
	s_nop 1
	v_cndmask_b32_e32 v207, v194, v207, vcc
	v_cmp_le_i32_e32 vcc, v3, v197
	v_subrev_u32_e32 v3, 30, v0
	s_nop 0
	v_cndmask_b32_e32 v206, v194, v206, vcc
	v_cmp_le_i32_e32 vcc, v3, v197
	v_subrev_u32_e32 v3, 61, v0
	s_nop 0
	v_cndmask_b32_e32 v223, v194, v223, vcc
	v_cmp_le_i32_e32 vcc, v3, v197
	v_subrev_u32_e32 v3, 29, v0
	s_nop 0
	v_cndmask_b32_e32 v208, v194, v208, vcc
	v_cmp_le_i32_e32 vcc, v3, v197
	v_subrev_u32_e32 v3, 60, v0
	s_nop 0
	v_cndmask_b32_e32 v224, v194, v224, vcc
	v_cmp_le_i32_e32 vcc, v3, v197
	v_subrev_u32_e32 v3, 28, v0
	s_nop 0
	v_cndmask_b32_e32 v209, v194, v209, vcc
	v_cmp_le_i32_e32 vcc, v3, v197
	v_subrev_u32_e32 v3, 55, v0
	s_nop 0
	v_cndmask_b32_e32 v225, v194, v225, vcc
	v_cmp_le_i32_e32 vcc, v3, v197
	v_subrev_u32_e32 v3, 23, v0
	s_nop 0
	v_cndmask_b32_e32 v210, v194, v210, vcc
	v_cmp_le_i32_e32 vcc, v3, v197
	v_subrev_u32_e32 v3, 54, v0
	s_nop 0
	v_cndmask_b32_e32 v226, v194, v226, vcc
	v_cmp_le_i32_e32 vcc, v3, v197
	v_subrev_u32_e32 v3, 22, v0
	s_nop 0
	v_cndmask_b32_e32 v211, v194, v211, vcc
	v_cmp_le_i32_e32 vcc, v3, v197
	v_subrev_u32_e32 v3, 53, v0
	s_nop 0
	v_cndmask_b32_e32 v227, v194, v227, vcc
	v_cmp_le_i32_e32 vcc, v3, v197
	v_subrev_u32_e32 v3, 21, v0
	s_nop 0
	v_cndmask_b32_e32 v212, v194, v212, vcc
	v_cmp_le_i32_e32 vcc, v3, v197
	v_subrev_u32_e32 v3, 52, v0
	s_nop 0
	v_cndmask_b32_e32 v228, v194, v228, vcc
	v_cmp_le_i32_e32 vcc, v3, v197
	v_subrev_u32_e32 v3, 20, v0
	s_nop 0
	v_cndmask_b32_e32 v213, v194, v213, vcc
	v_cmp_le_i32_e32 vcc, v3, v197
	v_subrev_u32_e32 v3, 47, v0
	s_nop 0
	v_cndmask_b32_e32 v229, v194, v229, vcc
	v_cmp_le_i32_e32 vcc, v3, v197
	v_add_u32_e32 v3, -15, v0
	s_nop 0
	v_cndmask_b32_e32 v214, v194, v214, vcc
	v_cmp_le_i32_e32 vcc, v3, v197
	v_subrev_u32_e32 v3, 46, v0
	s_nop 0
	v_cndmask_b32_e32 v230, v194, v230, vcc
	v_cmp_le_i32_e32 vcc, v3, v197
	v_add_u32_e32 v3, -14, v0
	s_nop 0
	v_cndmask_b32_e32 v215, v194, v215, vcc
	v_cmp_le_i32_e32 vcc, v3, v197
	v_subrev_u32_e32 v3, 45, v0
	s_nop 0
	v_cndmask_b32_e32 v231, v194, v231, vcc
	v_cmp_le_i32_e32 vcc, v3, v197
	v_add_u32_e32 v3, -13, v0
	s_nop 0
	v_cndmask_b32_e32 v216, v194, v216, vcc
	v_cmp_le_i32_e32 vcc, v3, v197
	v_subrev_u32_e32 v3, 44, v0
	s_nop 0
	v_cndmask_b32_e32 v232, v194, v232, vcc
	v_cmp_le_i32_e32 vcc, v3, v197
	v_add_u32_e32 v3, -12, v0
	s_nop 0
	v_cndmask_b32_e32 v217, v194, v217, vcc
	v_cmp_le_i32_e32 vcc, v3, v197
	v_subrev_u32_e32 v3, 39, v0
	s_nop 0
	v_cndmask_b32_e32 v233, v194, v233, vcc
	v_cmp_le_i32_e32 vcc, v3, v197
	v_add_u32_e32 v3, -7, v0
	s_nop 0
	v_cndmask_b32_e32 v218, v194, v218, vcc
	v_cmp_le_i32_e32 vcc, v3, v197
	v_subrev_u32_e32 v3, 38, v0
	s_nop 0
	v_cndmask_b32_e32 v234, v194, v234, vcc
	v_cmp_le_i32_e32 vcc, v3, v197
	v_add_u32_e32 v3, -6, v0
	s_nop 0
	v_cndmask_b32_e32 v219, v194, v219, vcc
	v_cmp_le_i32_e32 vcc, v3, v197
	v_subrev_u32_e32 v3, 37, v0
	s_nop 0
	v_cndmask_b32_e32 v235, v194, v235, vcc
	v_cmp_le_i32_e32 vcc, v3, v197
	v_add_u32_e32 v3, -5, v0
	s_nop 0
	v_cndmask_b32_e32 v220, v194, v220, vcc
	v_cmp_le_i32_e32 vcc, v3, v197
	v_subrev_u32_e32 v3, 36, v0
	v_add_u32_e32 v0, -4, v0
	v_cndmask_b32_e32 v236, v194, v236, vcc
	v_cmp_le_i32_e32 vcc, v3, v197
	s_nop 1
	v_cndmask_b32_e32 v221, v194, v221, vcc
	v_cmp_le_i32_e32 vcc, v0, v197
	s_nop 1
	v_cndmask_b32_e32 v237, v194, v237, vcc
.Lmaskdone_ba:
	s_mul_i32 s94, s93, 0x5000
	v_add_u32_e32 v4, s94, v203
	v_add_u32_e32 v5, 0xc800, v4
	s_setprio 1
	v_readfirstlane_b32 s32, v242
	s_cmpk_gt_u32 s32, 0xff
	s_cbranch_scc0 .Lprio_8
	s_setprio 3
.Lprio_8:
	ds_read_b64_tr_b16 v[238:239], v4 offset:51200
	ds_read_b64_tr_b16 v[240:241], v4 offset:53760
	ds_read_b64_tr_b16 v[244:245], v4 offset:51264
	ds_read_b64_tr_b16 v[246:247], v4 offset:53824
	ds_read_b64_tr_b16 v[248:249], v4 offset:51328
	ds_read_b64_tr_b16 v[250:251], v4 offset:53888
	ds_read_b64_tr_b16 v[8:9], v4 offset:51392
	ds_read_b64_tr_b16 v[10:11], v4 offset:53952
	ds_read_b64_tr_b16 v[12:13], v4 offset:56320
	ds_read_b64_tr_b16 v[14:15], v4 offset:58880
	s_waitcnt lgkmcnt(8)
	v_mfma_f32_32x32x16_bf16 v[64:79], v[96:99], v[238:241], v[64:79]
	ds_read_b64_tr_b16 v[238:239], v4 offset:56384
	ds_read_b64_tr_b16 v[240:241], v4 offset:58944
	s_waitcnt lgkmcnt(8)
	v_mfma_f32_32x32x16_bf16 v[48:63], v[96:99], v[244:247], v[48:63]
	ds_read_b64_tr_b16 v[244:245], v4 offset:56448
	ds_read_b64_tr_b16 v[246:247], v4 offset:59008
	s_waitcnt lgkmcnt(8)
	v_mfma_f32_32x32x16_bf16 v[32:47], v[96:99], v[248:251], v[32:47]
	ds_read_b64_tr_b16 v[248:249], v4 offset:56512
	ds_read_b64_tr_b16 v[250:251], v4 offset:59072
	s_waitcnt lgkmcnt(8)
	v_mfma_f32_32x32x16_bf16 v[16:31], v[96:99], v[8:11], v[16:31]
	ds_read_b64_tr_b16 v[8:9], v4 offset:61440
	ds_read_b64_tr_b16 v[10:11], v4 offset:64000
	v_max_f32_e32 v0, v206, v207
	v_max3_f32 v3, v208, v209, v223
	s_waitcnt lgkmcnt(8)
	v_mfma_f32_32x32x16_bf16 v[64:79], v[104:107], v[12:15], v[64:79]
	ds_read_b64_tr_b16 v[12:13], v4 offset:61504
	ds_read_b64_tr_b16 v[14:15], v4 offset:64064
	v_max3_f32 v0, v0, v222, v224
	v_max3_f32 v0, v0, v225, v210
	s_waitcnt lgkmcnt(8)
	v_mfma_f32_32x32x16_bf16 v[48:63], v[104:107], v[238:241], v[48:63]
	ds_read_b64_tr_b16 v[238:239], v4 offset:61568
	ds_read_b64_tr_b16 v[240:241], v4 offset:64128
	v_max3_f32 v3, v3, v212, v213
	s_waitcnt lgkmcnt(8)
	v_mfma_f32_32x32x16_bf16 v[32:47], v[104:107], v[244:247], v[32:47]
	ds_read_b64_tr_b16 v[244:245], v4 offset:61632
	ds_read_b64_tr_b16 v[246:247], v4 offset:64192
	v_max3_f32 v0, v0, v211, v226
	v_max3_f32 v3, v3, v228, v229
	s_waitcnt lgkmcnt(8)
	v_mfma_f32_32x32x16_bf16 v[16:31], v[104:107], v[248:251], v[16:31]
	ds_read_b64_tr_b16 v[248:249], v5 offset:15360
	ds_read_b64_tr_b16 v[250:251], v5 offset:17920
	v_max3_f32 v0, v0, v227, v214
	v_max3_f32 v3, v3, v216, v217
	s_waitcnt lgkmcnt(8)
	v_mfma_f32_32x32x16_bf16 v[64:79], v[112:115], v[8:11], v[64:79]
	ds_read_b64_tr_b16 v[8:9], v5 offset:15424
	ds_read_b64_tr_b16 v[10:11], v5 offset:17984
	v_max3_f32 v0, v0, v215, v230
	s_waitcnt lgkmcnt(8)
	v_mfma_f32_32x32x16_bf16 v[48:63], v[112:115], v[12:15], v[48:63]
	ds_read_b64_tr_b16 v[12:13], v5 offset:15488
	ds_read_b64_tr_b16 v[14:15], v5 offset:18048
	v_max3_f32 v3, v3, v232, v233
	v_max3_f32 v0, v0, v231, v218
	s_waitcnt lgkmcnt(8)
	v_mfma_f32_32x32x16_bf16 v[32:47], v[112:115], v[238:241], v[32:47]
	ds_read_b64_tr_b16 v[238:239], v5 offset:15552
	ds_read_b64_tr_b16 v[240:241], v5 offset:18112
	v_max3_f32 v3, v3, v220, v221
	v_max3_f32 v0, v0, v219, v234
	s_waitcnt lgkmcnt(8)
	v_mfma_f32_32x32x16_bf16 v[16:31], v[112:115], v[244:247], v[16:31]
	v_max3_f32 v3, v3, v236, v237
	s_waitcnt lgkmcnt(6)
	v_mfma_f32_32x32x16_bf16 v[64:79], v[120:123], v[248:251], v[64:79]
	v_max3_f32 v0, v0, v235, v3
	v_mov_b32_e32 v3, v0
	s_waitcnt lgkmcnt(4)
	v_mfma_f32_32x32x16_bf16 v[48:63], v[120:123], v[8:11], v[48:63]
	s_nop 1
	v_permlane32_swap_b32_e32 v0, v3
	s_waitcnt lgkmcnt(2)
	v_mfma_f32_32x32x16_bf16 v[32:47], v[120:123], v[12:15], v[32:47]
	v_max_f32_e32 v0, v0, v3
	s_waitcnt lgkmcnt(0)
	v_mfma_f32_32x32x16_bf16 v[16:31], v[120:123], v[238:241], v[16:31]
	s_setprio 0
	s_cmp_lg_u32 s75, 63
	s_cselect_b64 s[60:61], -1, 0
	s_cmp_eq_u32 s75, 63
	s_mov_b64 s[62:63], -1
	s_cbranch_scc1 .LBB0_2161_ba
	v_cmp_lt_f32_e32 vcc, s31, v0
	s_cbranch_vccz .LBB0_2170_ba
	v_max_f32_e32 v0, v0, v0
	v_max_f32_e32 v0, 0, v0

.Lnovis_ba:
	s_sub_i32 s61, s75, 0x7f
	s_cmp_gt_i32 s61, s25
	s_cbranch_scc1 .Lend_ba
	s_mul_i32 s94, s93, 0x5000
	v_add_u32_e32 v4, s94, v203
	v_add_u32_e32 v5, 0xc800, v4
	s_setprio 1
	v_readfirstlane_b32 s32, v242
	s_cmpk_gt_u32 s32, 0xff
	s_cbranch_scc0 .Lprio_7
	s_setprio 3
.Lprio_7:
	ds_read_b64_tr_b16 v[238:239], v4 offset:51200
	ds_read_b64_tr_b16 v[240:241], v4 offset:53760
	ds_read_b64_tr_b16 v[244:245], v4 offset:51264
	ds_read_b64_tr_b16 v[246:247], v4 offset:53824
	ds_read_b64_tr_b16 v[248:249], v4 offset:51328
	ds_read_b64_tr_b16 v[250:251], v4 offset:53888
	ds_read_b64_tr_b16 v[8:9], v4 offset:51392
	ds_read_b64_tr_b16 v[10:11], v4 offset:53952
	ds_read_b64_tr_b16 v[12:13], v4 offset:56320
	ds_read_b64_tr_b16 v[14:15], v4 offset:58880
	v_exp_f32_e32 v96, v96
	v_exp_f32_e32 v97, v97
	v_exp_f32_e32 v98, v98
	v_exp_f32_e32 v99, v99
	v_exp_f32_e32 v100, v100
	v_exp_f32_e32 v101, v101
	v_exp_f32_e32 v102, v102
	v_exp_f32_e32 v103, v103
	v_add_f32_e32 v252, v96, v97
	v_add_f32_e32 v253, v98, v99
	v_add_f32_e32 v254, v100, v101
	v_add_f32_e32 v205, v102, v103
	s_nop 0
	v_cvt_pk_bf16_f32 v96, v96, v97
	v_cvt_pk_bf16_f32 v97, v98, v99
	v_cvt_pk_bf16_f32 v98, v100, v101
	v_cvt_pk_bf16_f32 v99, v102, v103
	s_nop 1
	s_waitcnt lgkmcnt(8)
	v_mfma_f32_32x32x16_bf16 v[64:79], v[96:99], v[238:241], v[64:79]
	ds_read_b64_tr_b16 v[238:239], v4 offset:56384
	ds_read_b64_tr_b16 v[240:241], v4 offset:58944
	v_exp_f32_e32 v104, v104
	v_exp_f32_e32 v105, v105
	v_exp_f32_e32 v106, v106
	v_exp_f32_e32 v107, v107
	v_exp_f32_e32 v108, v108
	v_exp_f32_e32 v109, v109
	s_waitcnt lgkmcnt(8)
	v_mfma_f32_32x32x16_bf16 v[48:63], v[96:99], v[244:247], v[48:63]
	ds_read_b64_tr_b16 v[244:245], v4 offset:56448
	ds_read_b64_tr_b16 v[246:247], v4 offset:59008
	v_exp_f32_e32 v110, v110
	v_exp_f32_e32 v111, v111
	v_add_f32_e32 v252, v252, v104
	v_add_f32_e32 v253, v253, v105
	v_add_f32_e32 v254, v254, v106
	s_waitcnt lgkmcnt(8)
	v_mfma_f32_32x32x16_bf16 v[32:47], v[96:99], v[248:251], v[32:47]
	ds_read_b64_tr_b16 v[248:249], v4 offset:56512
	ds_read_b64_tr_b16 v[250:251], v4 offset:59072
	v_add_f32_e32 v205, v205, v107
	v_add_f32_e32 v252, v252, v108
	v_add_f32_e32 v253, v253, v109
	v_add_f32_e32 v254, v254, v110
	v_add_f32_e32 v205, v205, v111
	s_waitcnt lgkmcnt(8)
	v_mfma_f32_32x32x16_bf16 v[16:31], v[96:99], v[8:11], v[16:31]
	ds_read_b64_tr_b16 v[8:9], v4 offset:61440
	ds_read_b64_tr_b16 v[10:11], v4 offset:64000
	v_cvt_pk_bf16_f32 v104, v104, v105
	v_cvt_pk_bf16_f32 v105, v106, v107
	v_cvt_pk_bf16_f32 v106, v108, v109
	v_cvt_pk_bf16_f32 v107, v110, v111
	s_nop 1
	s_waitcnt lgkmcnt(8)
	v_mfma_f32_32x32x16_bf16 v[64:79], v[104:107], v[12:15], v[64:79]
	ds_read_b64_tr_b16 v[12:13], v4 offset:61504
	ds_read_b64_tr_b16 v[14:15], v4 offset:64064
	v_exp_f32_e32 v112, v112
	v_exp_f32_e32 v113, v113
	v_exp_f32_e32 v114, v114
	v_exp_f32_e32 v115, v115
	v_exp_f32_e32 v116, v116
	v_exp_f32_e32 v117, v117
	s_waitcnt lgkmcnt(8)
	v_mfma_f32_32x32x16_bf16 v[48:63], v[104:107], v[238:241], v[48:63]
	ds_read_b64_tr_b16 v[238:239], v4 offset:61568
	ds_read_b64_tr_b16 v[240:241], v4 offset:64128
	v_exp_f32_e32 v118, v118
	v_exp_f32_e32 v119, v119
	v_add_f32_e32 v252, v252, v112
	v_add_f32_e32 v253, v253, v113
	v_add_f32_e32 v254, v254, v114
	s_waitcnt lgkmcnt(8)
	v_mfma_f32_32x32x16_bf16 v[32:47], v[104:107], v[244:247], v[32:47]
	ds_read_b64_tr_b16 v[244:245], v4 offset:61632
	ds_read_b64_tr_b16 v[246:247], v4 offset:64192
	v_add_f32_e32 v205, v205, v115
	v_add_f32_e32 v252, v252, v116
	v_add_f32_e32 v253, v253, v117
	v_add_f32_e32 v254, v254, v118
	v_add_f32_e32 v205, v205, v119
	s_waitcnt lgkmcnt(8)
	v_mfma_f32_32x32x16_bf16 v[16:31], v[104:107], v[248:251], v[16:31]
	ds_read_b64_tr_b16 v[248:249], v5 offset:15360
	ds_read_b64_tr_b16 v[250:251], v5 offset:17920
	v_cvt_pk_bf16_f32 v112, v112, v113
	v_cvt_pk_bf16_f32 v113, v114, v115
	v_cvt_pk_bf16_f32 v114, v116, v117
	v_cvt_pk_bf16_f32 v115, v118, v119
	s_nop 1
	s_waitcnt lgkmcnt(8)
	v_mfma_f32_32x32x16_bf16 v[64:79], v[112:115], v[8:11], v[64:79]
	ds_read_b64_tr_b16 v[8:9], v5 offset:15424
	ds_read_b64_tr_b16 v[10:11], v5 offset:17984
	v_exp_f32_e32 v120, v120
	v_exp_f32_e32 v121, v121
	v_exp_f32_e32 v122, v122
	v_exp_f32_e32 v123, v123
	v_exp_f32_e32 v124, v124
	v_exp_f32_e32 v125, v125
	s_waitcnt lgkmcnt(8)
	v_mfma_f32_32x32x16_bf16 v[48:63], v[112:115], v[12:15], v[48:63]
	ds_read_b64_tr_b16 v[12:13], v5 offset:15488
	ds_read_b64_tr_b16 v[14:15], v5 offset:18048
	v_exp_f32_e32 v126, v126
	v_exp_f32_e32 v127, v127
	v_add_f32_e32 v252, v252, v120
	v_add_f32_e32 v253, v253, v121
	v_add_f32_e32 v254, v254, v122
	s_waitcnt lgkmcnt(8)
	v_mfma_f32_32x32x16_bf16 v[32:47], v[112:115], v[238:241], v[32:47]
	ds_read_b64_tr_b16 v[238:239], v5 offset:15552
	ds_read_b64_tr_b16 v[240:241], v5 offset:18112
	v_add_f32_e32 v205, v205, v123
	v_add_f32_e32 v252, v252, v124
	v_add_f32_e32 v253, v253, v125
	v_add_f32_e32 v254, v254, v126
	v_add_f32_e32 v205, v205, v127
	s_waitcnt lgkmcnt(8)
	v_mfma_f32_32x32x16_bf16 v[16:31], v[112:115], v[244:247], v[16:31]
	v_cvt_pk_bf16_f32 v120, v120, v121
	v_cvt_pk_bf16_f32 v121, v122, v123
	v_cvt_pk_bf16_f32 v122, v124, v125
	v_cvt_pk_bf16_f32 v123, v126, v127
	s_nop 1
	s_waitcnt lgkmcnt(6)
	v_mfma_f32_32x32x16_bf16 v[64:79], v[120:123], v[248:251], v[64:79]
	v_add_f32_e32 v252, v252, v253
	s_waitcnt lgkmcnt(4)
	v_mfma_f32_32x32x16_bf16 v[48:63], v[120:123], v[8:11], v[48:63]
	v_add_f32_e32 v254, v254, v205
	s_waitcnt lgkmcnt(2)
	v_mfma_f32_32x32x16_bf16 v[32:47], v[120:123], v[12:15], v[32:47]
	v_add_f32_e32 v252, v252, v254
	s_waitcnt lgkmcnt(0)
	v_mfma_f32_32x32x16_bf16 v[16:31], v[120:123], v[238:241], v[16:31]
	v_add_f32_e32 v2, v2, v252
	s_setprio 0

.Lprio_6:
	ds_read_b128 v[238:241], v0
	ds_read_b128 v[244:247], v0 offset:32
	ds_read_b128 v[248:251], v0 offset:12800
	ds_read_b128 v[8:11], v0 offset:12832
	ds_read_b128 v[12:15], v0 offset:64
	s_waitcnt lgkmcnt(4)
	v_mfma_f32_32x32x16_bf16 v[96:111], v[238:241], v[128:131], v[80:95]
	ds_read_b128 v[238:241], v0 offset:12864
	v_exp_f32_e32 v206, v206
	v_exp_f32_e32 v207, v207
	v_exp_f32_e32 v208, v208
	v_exp_f32_e32 v209, v209
	s_waitcnt lgkmcnt(4)
	v_mfma_f32_32x32x16_bf16 v[96:111], v[244:247], v[132:135], v[96:111]
	ds_read_b128 v[244:247], v0 offset:96
	v_exp_f32_e32 v210, v210
	v_exp_f32_e32 v211, v211
	v_exp_f32_e32 v212, v212
	s_waitcnt lgkmcnt(4)
	v_mfma_f32_32x32x16_bf16 v[112:127], v[248:251], v[128:131], v[80:95]
	ds_read_b128 v[248:251], v0 offset:12896
	v_exp_f32_e32 v213, v213
	v_exp_f32_e32 v214, v214
	v_exp_f32_e32 v215, v215
	s_waitcnt lgkmcnt(4)
	v_mfma_f32_32x32x16_bf16 v[112:127], v[8:11], v[132:135], v[112:127]
	ds_read_b128 v[8:11], v0 offset:128
	v_exp_f32_e32 v216, v216
	v_exp_f32_e32 v217, v217
	v_exp_f32_e32 v218, v218
	v_exp_f32_e32 v219, v219
	s_waitcnt lgkmcnt(4)
	v_mfma_f32_32x32x16_bf16 v[96:111], v[12:15], v[136:139], v[96:111]
	ds_read_b128 v[12:15], v0 offset:12928
	v_exp_f32_e32 v220, v220
	v_exp_f32_e32 v221, v221
	v_add_f32_e32 v252, v206, v207
	s_waitcnt lgkmcnt(4)
	v_mfma_f32_32x32x16_bf16 v[112:127], v[238:241], v[136:139], v[112:127]
	ds_read_b128 v[238:241], v0 offset:160
	v_add_f32_e32 v253, v208, v209
	v_add_f32_e32 v254, v210, v211
	v_add_f32_e32 v205, v212, v213
	s_waitcnt lgkmcnt(4)
	v_mfma_f32_32x32x16_bf16 v[96:111], v[244:247], v[140:143], v[96:111]
	ds_read_b128 v[244:247], v0 offset:12960
	v_cvt_pk_bf16_f32 v206, v206, v207
	v_cvt_pk_bf16_f32 v207, v208, v209
	v_cvt_pk_bf16_f32 v208, v210, v211
	v_cvt_pk_bf16_f32 v209, v212, v213
	s_waitcnt lgkmcnt(4)
	v_mfma_f32_32x32x16_bf16 v[112:127], v[248:251], v[140:143], v[112:127]
	ds_read_b128 v[248:251], v0 offset:192
	v_exp_f32_e32 v222, v222
	v_exp_f32_e32 v223, v223
	v_exp_f32_e32 v224, v224
	s_waitcnt lgkmcnt(4)
	v_mfma_f32_32x32x16_bf16 v[96:111], v[8:11], v[144:147], v[96:111]
	ds_read_b128 v[8:11], v0 offset:12992
	v_exp_f32_e32 v225, v225
	v_exp_f32_e32 v226, v226
	v_exp_f32_e32 v227, v227
	s_waitcnt lgkmcnt(4)
	v_mfma_f32_32x32x16_bf16 v[112:127], v[12:15], v[144:147], v[112:127]
	ds_read_b128 v[12:15], v0 offset:224
	v_exp_f32_e32 v228, v228
	v_exp_f32_e32 v229, v229
	v_add_f32_e32 v252, v252, v214
	v_add_f32_e32 v253, v253, v215
	s_waitcnt lgkmcnt(4)
	v_mfma_f32_32x32x16_bf16 v[96:111], v[238:241], v[148:151], v[96:111]
	ds_read_b128 v[238:241], v0 offset:13024
	v_add_f32_e32 v254, v254, v216
	v_add_f32_e32 v205, v205, v217
	v_add_f32_e32 v252, v252, v218
	s_waitcnt lgkmcnt(4)
	v_mfma_f32_32x32x16_bf16 v[112:127], v[244:247], v[148:151], v[112:127]
	ds_read_b128 v[244:247], v0 offset:256
	v_add_f32_e32 v253, v253, v219
	v_add_f32_e32 v254, v254, v220
	v_add_f32_e32 v205, v205, v221
	s_waitcnt lgkmcnt(4)
	v_mfma_f32_32x32x16_bf16 v[96:111], v[248:251], v[152:155], v[96:111]
	ds_read_b128 v[248:251], v0 offset:13056
	v_cvt_pk_bf16_f32 v214, v214, v215
	v_cvt_pk_bf16_f32 v215, v216, v217
	v_cvt_pk_bf16_f32 v216, v218, v219
	v_cvt_pk_bf16_f32 v217, v220, v221
	s_waitcnt lgkmcnt(4)
	v_mfma_f32_32x32x16_bf16 v[112:127], v[8:11], v[152:155], v[112:127]
	ds_read_b128 v[8:11], v0 offset:288
	v_exp_f32_e32 v230, v230
	v_exp_f32_e32 v231, v231
	v_exp_f32_e32 v232, v232
	s_waitcnt lgkmcnt(4)
	v_mfma_f32_32x32x16_bf16 v[96:111], v[12:15], v[156:159], v[96:111]
	ds_read_b128 v[12:15], v0 offset:13088
	v_exp_f32_e32 v233, v233
	v_exp_f32_e32 v234, v234
	v_exp_f32_e32 v235, v235
	s_waitcnt lgkmcnt(4)
	v_mfma_f32_32x32x16_bf16 v[112:127], v[238:241], v[156:159], v[112:127]
	ds_read_b128 v[238:241], v0 offset:320
	v_exp_f32_e32 v236, v236
	v_exp_f32_e32 v237, v237
	v_add_f32_e32 v252, v252, v222
	v_add_f32_e32 v253, v253, v223
	s_waitcnt lgkmcnt(4)
	v_mfma_f32_32x32x16_bf16 v[96:111], v[244:247], v[160:163], v[96:111]
	ds_read_b128 v[244:247], v0 offset:13120
	v_add_f32_e32 v254, v254, v224
	v_add_f32_e32 v205, v205, v225
	v_add_f32_e32 v252, v252, v226
	s_waitcnt lgkmcnt(4)
	v_mfma_f32_32x32x16_bf16 v[112:127], v[248:251], v[160:163], v[112:127]
	ds_read_b128 v[248:251], v0 offset:352
	v_add_f32_e32 v253, v253, v227
	v_add_f32_e32 v254, v254, v228
	v_add_f32_e32 v205, v205, v229
	s_waitcnt lgkmcnt(4)
	v_mfma_f32_32x32x16_bf16 v[96:111], v[8:11], v[164:167], v[96:111]
	ds_read_b128 v[8:11], v0 offset:13152
	v_cvt_pk_bf16_f32 v222, v222, v223
	v_cvt_pk_bf16_f32 v223, v224, v225
	v_cvt_pk_bf16_f32 v224, v226, v227
	v_cvt_pk_bf16_f32 v225, v228, v229
	s_waitcnt lgkmcnt(4)
	v_mfma_f32_32x32x16_bf16 v[112:127], v[12:15], v[164:167], v[112:127]
	v_add_f32_e32 v252, v252, v230
	v_add_f32_e32 v253, v253, v231
	v_add_f32_e32 v254, v254, v232
	s_waitcnt lgkmcnt(3)
	v_mfma_f32_32x32x16_bf16 v[96:111], v[238:241], v[168:171], v[96:111]
	v_add_f32_e32 v205, v205, v233
	v_add_f32_e32 v252, v252, v234
	v_add_f32_e32 v253, v253, v235
	s_waitcnt lgkmcnt(2)
	v_mfma_f32_32x32x16_bf16 v[112:127], v[244:247], v[168:171], v[112:127]
	v_add_f32_e32 v254, v254, v236
	v_add_f32_e32 v205, v205, v237
	v_cvt_pk_bf16_f32 v230, v230, v231
	v_cvt_pk_bf16_f32 v231, v232, v233
	s_waitcnt lgkmcnt(1)
	v_mfma_f32_32x32x16_bf16 v[96:111], v[248:251], v[172:175], v[96:111]
	v_cvt_pk_bf16_f32 v232, v234, v235
	v_cvt_pk_bf16_f32 v233, v236, v237
	v_add_f32_e32 v252, v252, v253
	s_waitcnt lgkmcnt(0)
	v_mfma_f32_32x32x16_bf16 v[112:127], v[8:11], v[172:175], v[112:127]
	v_add_f32_e32 v254, v254, v205
	v_add_f32_e32 v252, v252, v254
	v_add_f32_e32 v2, v2, v252
	s_setprio 0
	s_cmp_le_i32 s75, s68
	s_cbranch_scc1 .Lmaskdone_ab
	v_add_u32_e32 v0, s75, v201
	v_subrev_u32_e32 v4, 31, v0
	v_subrev_u32_e32 v3, 63, v0
	v_cmp_le_i32_e32 vcc, v4, v197
	s_nop 4
	v_cndmask_b32_e32 v112, v194, v112, vcc
	v_cmp_lt_i32_e32 vcc, v3, v197
	s_nop 1
	v_cndmask_b32_e32 v97, v194, v97, vcc
	v_cmp_le_i32_e32 vcc, v3, v197
	v_subrev_u32_e32 v3, 30, v0
	s_nop 0
	v_cndmask_b32_e32 v96, v194, v96, vcc
	v_cmp_le_i32_e32 vcc, v3, v197
	v_subrev_u32_e32 v3, 61, v0
	s_nop 0
	v_cndmask_b32_e32 v113, v194, v113, vcc
	v_cmp_le_i32_e32 vcc, v3, v197
	v_subrev_u32_e32 v3, 29, v0
	s_nop 0
	v_cndmask_b32_e32 v98, v194, v98, vcc
	v_cmp_le_i32_e32 vcc, v3, v197
	v_subrev_u32_e32 v3, 60, v0
	s_nop 0
	v_cndmask_b32_e32 v114, v194, v114, vcc
	v_cmp_le_i32_e32 vcc, v3, v197
	v_subrev_u32_e32 v3, 28, v0
	s_nop 0
	v_cndmask_b32_e32 v99, v194, v99, vcc
	v_cmp_le_i32_e32 vcc, v3, v197
	v_subrev_u32_e32 v3, 55, v0
	s_nop 0
	v_cndmask_b32_e32 v115, v194, v115, vcc
	v_cmp_le_i32_e32 vcc, v3, v197
	v_subrev_u32_e32 v3, 23, v0
	s_nop 0
	v_cndmask_b32_e32 v100, v194, v100, vcc
	v_cmp_le_i32_e32 vcc, v3, v197
	v_subrev_u32_e32 v3, 54, v0
	s_nop 0
	v_cndmask_b32_e32 v116, v194, v116, vcc
	v_cmp_le_i32_e32 vcc, v3, v197
	v_subrev_u32_e32 v3, 22, v0
	s_nop 0
	v_cndmask_b32_e32 v101, v194, v101, vcc
	v_cmp_le_i32_e32 vcc, v3, v197
	v_subrev_u32_e32 v3, 53, v0
	s_nop 0
	v_cndmask_b32_e32 v117, v194, v117, vcc
	v_cmp_le_i32_e32 vcc, v3, v197
	v_subrev_u32_e32 v3, 21, v0
	s_nop 0
	v_cndmask_b32_e32 v102, v194, v102, vcc
	v_cmp_le_i32_e32 vcc, v3, v197
	v_subrev_u32_e32 v3, 52, v0
	s_nop 0
	v_cndmask_b32_e32 v118, v194, v118, vcc
	v_cmp_le_i32_e32 vcc, v3, v197
	v_subrev_u32_e32 v3, 20, v0
	s_nop 0
	v_cndmask_b32_e32 v103, v194, v103, vcc
	v_cmp_le_i32_e32 vcc, v3, v197
	v_subrev_u32_e32 v3, 47, v0
	s_nop 0
	v_cndmask_b32_e32 v119, v194, v119, vcc
	v_cmp_le_i32_e32 vcc, v3, v197
	v_add_u32_e32 v3, -15, v0
	s_nop 0
	v_cndmask_b32_e32 v104, v194, v104, vcc
	v_cmp_le_i32_e32 vcc, v3, v197
	v_subrev_u32_e32 v3, 46, v0
	s_nop 0
	v_cndmask_b32_e32 v120, v194, v120, vcc
	v_cmp_le_i32_e32 vcc, v3, v197
	v_add_u32_e32 v3, -14, v0
	s_nop 0
	v_cndmask_b32_e32 v105, v194, v105, vcc
	v_cmp_le_i32_e32 vcc, v3, v197
	v_subrev_u32_e32 v3, 45, v0
	s_nop 0
	v_cndmask_b32_e32 v121, v194, v121, vcc
	v_cmp_le_i32_e32 vcc, v3, v197
	v_add_u32_e32 v3, -13, v0
	s_nop 0
	v_cndmask_b32_e32 v106, v194, v106, vcc
	v_cmp_le_i32_e32 vcc, v3, v197
	v_subrev_u32_e32 v3, 44, v0
	s_nop 0
	v_cndmask_b32_e32 v122, v194, v122, vcc
	v_cmp_le_i32_e32 vcc, v3, v197
	v_add_u32_e32 v3, -12, v0
	s_nop 0
	v_cndmask_b32_e32 v107, v194, v107, vcc
	v_cmp_le_i32_e32 vcc, v3, v197
	v_subrev_u32_e32 v3, 39, v0
	s_nop 0
	v_cndmask_b32_e32 v123, v194, v123, vcc
	v_cmp_le_i32_e32 vcc, v3, v197
	v_add_u32_e32 v3, -7, v0
	s_nop 0
	v_cndmask_b32_e32 v108, v194, v108, vcc
	v_cmp_le_i32_e32 vcc, v3, v197
	v_subrev_u32_e32 v3, 38, v0
	s_nop 0
	v_cndmask_b32_e32 v124, v194, v124, vcc
	v_cmp_le_i32_e32 vcc, v3, v197
	v_add_u32_e32 v3, -6, v0
	s_nop 0
	v_cndmask_b32_e32 v109, v194, v109, vcc
	v_cmp_le_i32_e32 vcc, v3, v197
	v_subrev_u32_e32 v3, 37, v0
	s_nop 0
	v_cndmask_b32_e32 v125, v194, v125, vcc
	v_cmp_le_i32_e32 vcc, v3, v197
	v_add_u32_e32 v3, -5, v0
	s_nop 0
	v_cndmask_b32_e32 v110, v194, v110, vcc
	v_cmp_le_i32_e32 vcc, v3, v197
	v_subrev_u32_e32 v3, 36, v0
	v_add_u32_e32 v0, -4, v0
	v_cndmask_b32_e32 v126, v194, v126, vcc
	v_cmp_le_i32_e32 vcc, v3, v197
	s_nop 1
	v_cndmask_b32_e32 v111, v194, v111, vcc
	v_cmp_le_i32_e32 vcc, v0, v197
	s_nop 1
	v_cndmask_b32_e32 v127, v194, v127, vcc

.Lprio_5:
	ds_read_b64_tr_b16 v[238:239], v4 offset:51200
	ds_read_b64_tr_b16 v[240:241], v4 offset:53760
	ds_read_b64_tr_b16 v[244:245], v4 offset:51264
	ds_read_b64_tr_b16 v[246:247], v4 offset:53824
	ds_read_b64_tr_b16 v[248:249], v4 offset:51328
	ds_read_b64_tr_b16 v[250:251], v4 offset:53888
	ds_read_b64_tr_b16 v[8:9], v4 offset:51392
	ds_read_b64_tr_b16 v[10:11], v4 offset:53952
	ds_read_b64_tr_b16 v[12:13], v4 offset:56320
	ds_read_b64_tr_b16 v[14:15], v4 offset:58880
	s_waitcnt lgkmcnt(8)
	v_mfma_f32_32x32x16_bf16 v[64:79], v[206:209], v[238:241], v[64:79]
	ds_read_b64_tr_b16 v[238:239], v4 offset:56384
	ds_read_b64_tr_b16 v[240:241], v4 offset:58944
	s_waitcnt lgkmcnt(8)
	v_mfma_f32_32x32x16_bf16 v[48:63], v[206:209], v[244:247], v[48:63]
	ds_read_b64_tr_b16 v[244:245], v4 offset:56448
	ds_read_b64_tr_b16 v[246:247], v4 offset:59008
	s_waitcnt lgkmcnt(8)
	v_mfma_f32_32x32x16_bf16 v[32:47], v[206:209], v[248:251], v[32:47]
	ds_read_b64_tr_b16 v[248:249], v4 offset:56512
	ds_read_b64_tr_b16 v[250:251], v4 offset:59072
	s_waitcnt lgkmcnt(8)
	v_mfma_f32_32x32x16_bf16 v[16:31], v[206:209], v[8:11], v[16:31]
	ds_read_b64_tr_b16 v[8:9], v4 offset:61440
	ds_read_b64_tr_b16 v[10:11], v4 offset:64000
	v_max_f32_e32 v0, v96, v97
	v_max3_f32 v3, v98, v99, v113
	s_waitcnt lgkmcnt(8)
	v_mfma_f32_32x32x16_bf16 v[64:79], v[214:217], v[12:15], v[64:79]
	ds_read_b64_tr_b16 v[12:13], v4 offset:61504
	ds_read_b64_tr_b16 v[14:15], v4 offset:64064
	v_max3_f32 v0, v0, v112, v114
	v_max3_f32 v0, v0, v115, v100
	s_waitcnt lgkmcnt(8)
	v_mfma_f32_32x32x16_bf16 v[48:63], v[214:217], v[238:241], v[48:63]
	ds_read_b64_tr_b16 v[238:239], v4 offset:61568
	ds_read_b64_tr_b16 v[240:241], v4 offset:64128
	v_max3_f32 v3, v3, v102, v103
	s_waitcnt lgkmcnt(8)
	v_mfma_f32_32x32x16_bf16 v[32:47], v[214:217], v[244:247], v[32:47]
	ds_read_b64_tr_b16 v[244:245], v4 offset:61632
	ds_read_b64_tr_b16 v[246:247], v4 offset:64192
	v_max3_f32 v0, v0, v101, v116
	v_max3_f32 v3, v3, v118, v119
	s_waitcnt lgkmcnt(8)
	v_mfma_f32_32x32x16_bf16 v[16:31], v[214:217], v[248:251], v[16:31]
	ds_read_b64_tr_b16 v[248:249], v5 offset:15360
	ds_read_b64_tr_b16 v[250:251], v5 offset:17920
	v_max3_f32 v0, v0, v117, v104
	v_max3_f32 v3, v3, v106, v107
	s_waitcnt lgkmcnt(8)
	v_mfma_f32_32x32x16_bf16 v[64:79], v[222:225], v[8:11], v[64:79]
	ds_read_b64_tr_b16 v[8:9], v5 offset:15424
	ds_read_b64_tr_b16 v[10:11], v5 offset:17984
	v_max3_f32 v0, v0, v105, v120
	s_waitcnt lgkmcnt(8)
	v_mfma_f32_32x32x16_bf16 v[48:63], v[222:225], v[12:15], v[48:63]
	ds_read_b64_tr_b16 v[12:13], v5 offset:15488
	ds_read_b64_tr_b16 v[14:15], v5 offset:18048
	v_max3_f32 v3, v3, v122, v123
	v_max3_f32 v0, v0, v121, v108
	s_waitcnt lgkmcnt(8)
	v_mfma_f32_32x32x16_bf16 v[32:47], v[222:225], v[238:241], v[32:47]
	ds_read_b64_tr_b16 v[238:239], v5 offset:15552
	ds_read_b64_tr_b16 v[240:241], v5 offset:18112
	v_max3_f32 v3, v3, v110, v111
	v_max3_f32 v0, v0, v109, v124
	s_waitcnt lgkmcnt(8)
	v_mfma_f32_32x32x16_bf16 v[16:31], v[222:225], v[244:247], v[16:31]
	v_max3_f32 v3, v3, v126, v127
	s_waitcnt lgkmcnt(6)
	v_mfma_f32_32x32x16_bf16 v[64:79], v[230:233], v[248:251], v[64:79]
	v_max3_f32 v0, v0, v125, v3
	v_mov_b32_e32 v3, v0
	s_waitcnt lgkmcnt(4)
	v_mfma_f32_32x32x16_bf16 v[48:63], v[230:233], v[8:11], v[48:63]
	s_nop 1
	v_permlane32_swap_b32_e32 v0, v3
	s_waitcnt lgkmcnt(2)
	v_mfma_f32_32x32x16_bf16 v[32:47], v[230:233], v[12:15], v[32:47]
	v_max_f32_e32 v0, v0, v3
	s_waitcnt lgkmcnt(0)
	v_mfma_f32_32x32x16_bf16 v[16:31], v[230:233], v[238:241], v[16:31]
	s_setprio 0
	s_cmp_lg_u32 s75, 63
	s_cselect_b64 s[60:61], -1, 0
	s_cmp_eq_u32 s75, 63
	s_mov_b64 s[62:63], -1
	s_cbranch_scc1 .LBB0_2161_ab
	v_cmp_lt_f32_e32 vcc, s31, v0
	s_cbranch_vccz .LBB0_2170_ab
	v_max_f32_e32 v0, v0, v0
	v_max_f32_e32 v0, 0, v0

.Lprio_4:
	ds_read_b64_tr_b16 v[238:239], v4 offset:51200
	ds_read_b64_tr_b16 v[240:241], v4 offset:53760
	ds_read_b64_tr_b16 v[244:245], v4 offset:51264
	ds_read_b64_tr_b16 v[246:247], v4 offset:53824
	ds_read_b64_tr_b16 v[248:249], v4 offset:51328
	ds_read_b64_tr_b16 v[250:251], v4 offset:53888
	ds_read_b64_tr_b16 v[8:9], v4 offset:51392
	ds_read_b64_tr_b16 v[10:11], v4 offset:53952
	ds_read_b64_tr_b16 v[12:13], v4 offset:56320
	ds_read_b64_tr_b16 v[14:15], v4 offset:58880
	v_exp_f32_e32 v206, v206
	v_exp_f32_e32 v207, v207
	v_exp_f32_e32 v208, v208
	v_exp_f32_e32 v209, v209
	v_exp_f32_e32 v210, v210
	v_exp_f32_e32 v211, v211
	v_exp_f32_e32 v212, v212
	v_exp_f32_e32 v213, v213
	v_add_f32_e32 v252, v206, v207
	v_add_f32_e32 v253, v208, v209
	v_add_f32_e32 v254, v210, v211
	v_add_f32_e32 v205, v212, v213
	s_nop 0
	v_cvt_pk_bf16_f32 v206, v206, v207
	v_cvt_pk_bf16_f32 v207, v208, v209
	v_cvt_pk_bf16_f32 v208, v210, v211
	v_cvt_pk_bf16_f32 v209, v212, v213
	s_nop 1
	s_waitcnt lgkmcnt(8)
	v_mfma_f32_32x32x16_bf16 v[64:79], v[206:209], v[238:241], v[64:79]
	ds_read_b64_tr_b16 v[238:239], v4 offset:56384
	ds_read_b64_tr_b16 v[240:241], v4 offset:58944
	v_exp_f32_e32 v214, v214
	v_exp_f32_e32 v215, v215
	v_exp_f32_e32 v216, v216
	v_exp_f32_e32 v217, v217
	v_exp_f32_e32 v218, v218
	v_exp_f32_e32 v219, v219
	s_waitcnt lgkmcnt(8)
	v_mfma_f32_32x32x16_bf16 v[48:63], v[206:209], v[244:247], v[48:63]
	ds_read_b64_tr_b16 v[244:245], v4 offset:56448
	ds_read_b64_tr_b16 v[246:247], v4 offset:59008
	v_exp_f32_e32 v220, v220
	v_exp_f32_e32 v221, v221
	v_add_f32_e32 v252, v252, v214
	v_add_f32_e32 v253, v253, v215
	v_add_f32_e32 v254, v254, v216
	s_waitcnt lgkmcnt(8)
	v_mfma_f32_32x32x16_bf16 v[32:47], v[206:209], v[248:251], v[32:47]
	ds_read_b64_tr_b16 v[248:249], v4 offset:56512
	ds_read_b64_tr_b16 v[250:251], v4 offset:59072
	v_add_f32_e32 v205, v205, v217
	v_add_f32_e32 v252, v252, v218
	v_add_f32_e32 v253, v253, v219
	v_add_f32_e32 v254, v254, v220
	v_add_f32_e32 v205, v205, v221
	s_waitcnt lgkmcnt(8)
	v_mfma_f32_32x32x16_bf16 v[16:31], v[206:209], v[8:11], v[16:31]
	ds_read_b64_tr_b16 v[8:9], v4 offset:61440
	ds_read_b64_tr_b16 v[10:11], v4 offset:64000
	v_cvt_pk_bf16_f32 v214, v214, v215
	v_cvt_pk_bf16_f32 v215, v216, v217
	v_cvt_pk_bf16_f32 v216, v218, v219
	v_cvt_pk_bf16_f32 v217, v220, v221
	s_nop 1
	s_waitcnt lgkmcnt(8)
	v_mfma_f32_32x32x16_bf16 v[64:79], v[214:217], v[12:15], v[64:79]
	ds_read_b64_tr_b16 v[12:13], v4 offset:61504
	ds_read_b64_tr_b16 v[14:15], v4 offset:64064
	v_exp_f32_e32 v222, v222
	v_exp_f32_e32 v223, v223
	v_exp_f32_e32 v224, v224
	v_exp_f32_e32 v225, v225
	v_exp_f32_e32 v226, v226
	v_exp_f32_e32 v227, v227
	s_waitcnt lgkmcnt(8)
	v_mfma_f32_32x32x16_bf16 v[48:63], v[214:217], v[238:241], v[48:63]
	ds_read_b64_tr_b16 v[238:239], v4 offset:61568
	ds_read_b64_tr_b16 v[240:241], v4 offset:64128
	v_exp_f32_e32 v228, v228
	v_exp_f32_e32 v229, v229
	v_add_f32_e32 v252, v252, v222
	v_add_f32_e32 v253, v253, v223
	v_add_f32_e32 v254, v254, v224
	s_waitcnt lgkmcnt(8)
	v_mfma_f32_32x32x16_bf16 v[32:47], v[214:217], v[244:247], v[32:47]
	ds_read_b64_tr_b16 v[244:245], v4 offset:61632
	ds_read_b64_tr_b16 v[246:247], v4 offset:64192
	v_add_f32_e32 v205, v205, v225
	v_add_f32_e32 v252, v252, v226
	v_add_f32_e32 v253, v253, v227
	v_add_f32_e32 v254, v254, v228
	v_add_f32_e32 v205, v205, v229
	s_waitcnt lgkmcnt(8)
	v_mfma_f32_32x32x16_bf16 v[16:31], v[214:217], v[248:251], v[16:31]
	ds_read_b64_tr_b16 v[248:249], v5 offset:15360
	ds_read_b64_tr_b16 v[250:251], v5 offset:17920
	v_cvt_pk_bf16_f32 v222, v222, v223
	v_cvt_pk_bf16_f32 v223, v224, v225
	v_cvt_pk_bf16_f32 v224, v226, v227
	v_cvt_pk_bf16_f32 v225, v228, v229
	s_nop 1
	s_waitcnt lgkmcnt(8)
	v_mfma_f32_32x32x16_bf16 v[64:79], v[222:225], v[8:11], v[64:79]
	ds_read_b64_tr_b16 v[8:9], v5 offset:15424
	ds_read_b64_tr_b16 v[10:11], v5 offset:17984
	v_exp_f32_e32 v230, v230
	v_exp_f32_e32 v231, v231
	v_exp_f32_e32 v232, v232
	v_exp_f32_e32 v233, v233
	v_exp_f32_e32 v234, v234
	v_exp_f32_e32 v235, v235
	s_waitcnt lgkmcnt(8)
	v_mfma_f32_32x32x16_bf16 v[48:63], v[222:225], v[12:15], v[48:63]
	ds_read_b64_tr_b16 v[12:13], v5 offset:15488
	ds_read_b64_tr_b16 v[14:15], v5 offset:18048
	v_exp_f32_e32 v236, v236
	v_exp_f32_e32 v237, v237
	v_add_f32_e32 v252, v252, v230
	v_add_f32_e32 v253, v253, v231
	v_add_f32_e32 v254, v254, v232
	s_waitcnt lgkmcnt(8)
	v_mfma_f32_32x32x16_bf16 v[32:47], v[222:225], v[238:241], v[32:47]
	ds_read_b64_tr_b16 v[238:239], v5 offset:15552
	ds_read_b64_tr_b16 v[240:241], v5 offset:18112
	v_add_f32_e32 v205, v205, v233
	v_add_f32_e32 v252, v252, v234
	v_add_f32_e32 v253, v253, v235
	v_add_f32_e32 v254, v254, v236
	v_add_f32_e32 v205, v205, v237
	s_waitcnt lgkmcnt(8)
	v_mfma_f32_32x32x16_bf16 v[16:31], v[222:225], v[244:247], v[16:31]
	v_cvt_pk_bf16_f32 v230, v230, v231
	v_cvt_pk_bf16_f32 v231, v232, v233
	v_cvt_pk_bf16_f32 v232, v234, v235
	v_cvt_pk_bf16_f32 v233, v236, v237
	s_nop 1
	s_waitcnt lgkmcnt(6)
	v_mfma_f32_32x32x16_bf16 v[64:79], v[230:233], v[248:251], v[64:79]
	v_add_f32_e32 v252, v252, v253
	s_waitcnt lgkmcnt(4)
	v_mfma_f32_32x32x16_bf16 v[48:63], v[230:233], v[8:11], v[48:63]
	v_add_f32_e32 v254, v254, v205
	s_waitcnt lgkmcnt(2)
	v_mfma_f32_32x32x16_bf16 v[32:47], v[230:233], v[12:15], v[32:47]
	v_add_f32_e32 v252, v252, v254
	s_waitcnt lgkmcnt(0)
	v_mfma_f32_32x32x16_bf16 v[16:31], v[230:233], v[238:241], v[16:31]
	v_add_f32_e32 v2, v2, v252
	s_setprio 0

; #define ATT_BAR() asm volatile("s_waitcnt lgkmcnt(0)\n\ts_barrier" ::: "memory")
; #define ATT_BAR() asm volatile("s_waitcnt vmcnt(0) lgkmcnt(0)\n\ts_barrier" ::: "memory")
; template <int DQK>
; __device__ __forceinline__ void attn_pass4(LAS unsigned char* lds, const bf16* Qp, int qpitch, const bf16* Kp, int kpitch, const bf16* Vp, int vpitch, int q0, f32x16 (&o)[4], float (&rl)[16]) {
;     ...
;         for (int t = 0; t < NT; ++t) {
;             const int vnext = ATT_VNEXT(vcur);
;             if (t + 1 < NT) ATT_DMA(t + 1, (t + 1) & 1, vnext);
;             if (t > 0 && ATT_VIS(t - 1)) ATT_B(vprev);
;             if (ATT_VIS(t)) ATT_A(t);
;             vprev = vcur; vcur = vnext;
;             ATT_BAR();
;         }
;         if (ATT_VIS(NT - 1)) ATT_B(vprev);
.Lend_fin:
	s_add_i32 s75, s75, 64
	s_add_u32 s58, s58, 0x20000
	s_addc_u32 s59, s59, 0
	s_add_u32 s56, s56, 0x30000
	s_waitcnt vmcnt(0) lgkmcnt(0)
	s_barrier
	s_addc_u32 s57, s57, 0
	s_cmp_eq_u32 s69, s77
	s_mov_b32 s93, s78
	s_mov_b32 s78, s76
	s_mov_b32 s60, s77
	s_sub_i32 s61, s75, 0x7f
	s_cmp_gt_i32 s61, s25
	s_cbranch_scc1 .Lpipe_done
	s_mul_i32 s94, s93, 0x5000
	v_add_u32_e32 v4, s94, v203
	v_add_u32_e32 v5, 0xc800, v4
	s_setprio 1
	v_readfirstlane_b32 s32, v242
	s_cmpk_gt_u32 s32, 0xff
	s_cbranch_scc0 .Lprio_0
	s_setprio 3
